# up GEMM K-loop: B0 fragment ds_reads moved one phase earlier (into the read-free phases 4/8 load segments, covered by a new vmcnt(10) in phases 3/7) to balance LDS traffic per phase 8/4/8/4 instead of
# speedup vs baseline: 1.0042x; 1.0042x over previous
; #define G8_STAGE(bufoff, gbase) do { _Pragma("unroll") for (int _i = 0; _i < 2; ++_i) \
;     __builtin_amdgcn_global_load_lds((const unsigned*)((const char*)(gbase) + voffA[_i]), (LAS unsigned*)(lds + (bufoff) + ldsw + _i * 8192), 16, 0, 0); } while (0)
; #define G8_LDA(dst, b, h) do { _Pragma("unroll") for (int m = 0; m < 4; ++m) _Pragma("unroll") for (int k = 0; k < 2; ++k) dst[m][k] = *(const LAS h16x8*)(lds + G8_SA(b, h) + aoff + m * 2048 + k * 1024); } while (0)
; #define G8_LDB(dst, b, h) do { _Pragma("unroll") for (int n = 0; n < 2; ++n) _Pragma("unroll") for (int k = 0; k < 2; ++k) dst[n][k] = *(const LAS h16x8*)(lds + G8_SB(b, h) + boff + n * 2048 + k * 1024); } while (0)
; #define G8_MMA(ai, bj, At, Bt_) do { __builtin_amdgcn_s_setprio(1); _Pragma("unroll") for (int m = 0; m < 4; ++m) _Pragma("unroll") for (int n = 0; n < 2; ++n) _Pragma("unroll") for (int k = 0; k < 2; ++k) \
;     acc[ai][bj][m][n] = __builtin_amdgcn_mfma_f32_16x16x32_f16(Bt_[n][k], At[m][k], acc[ai][bj][m][n], 0, 0, 0); __builtin_amdgcn_s_setprio(0); } while (0)
; #define G8_WAIT_L(n) asm volatile("s_waitcnt lgkmcnt(" #n ")" ::: "memory")
; #define G8_BAR __builtin_amdgcn_s_barrier()
; template <class Epi>
; __device__ __forceinline__ void gemm_phase(LAS unsigned char* lds, const h16* A, const h16* Bt, int K, const Order& S, const Epi& E) {
;     ...
;     const bool has_next = S.next(ui + 1, nxt);
;     const char* nA = has_next ? (const char*)A + (size_t)nxt.pm * tstep : cA;
;     const char* nB = has_next ? (const char*)Bt + (size_t)nxt.pn * tstep : cB;
;     for (int t = 0; t < nt; t += 2) {
;       const bool last = (t == nt - 2);
;       const char* a1 = cA + (size_t)(t + 1) * kstep;
;       const char* a2 = last ? nA : cA + (size_t)(t + 2) * kstep;
;       const char* b2 = last ? nB : cB + (size_t)(t + 2) * kstep;
;       const char* a3 = a2 + kstep;
;       const char* b3 = b2 + kstep;
;       if (Epi::MID_T >= 0 && t == Epi::MID_T) E.mid(acc, ui, wr, fr);
;       G8_LDB(B0, 0, 0); G8_SCHED; G8_LDA(At, 0, 0); G8_STAGE(G8_SA(1, 1), a1 + hstep);
;       G8_WAIT_L(8); G8_BAR; G8_WAIT_L(0); G8_MMA(0, 0, At, B0); G8_BAR; G8_SCHED;
;     ...
;     for (int a = 0; a < 2; ++a)
; #pragma unroll
;       for (int b = 0; b < 2; ++b)
; #pragma unroll
;         for (int m = 0; m < 4; ++m)
; #pragma unroll
;           for (int n = 0; n < 2; ++n) acc[a][b][m][n] = (f32x4){0.f, 0.f, 0.f, 0.f};
.LBB0_2472:
	v_mov_b64_e32 v[2:3], 0x800
	s_ashr_i32 s13, s12, 31
	v_cmp_lt_i64_e32 vcc, s[14:15], v[2:3]
	s_lshl_b64 s[14:15], s[12:13], 19
	s_add_u32 s14, s3, s14
	s_addc_u32 s15, s24, s15
	s_and_b64 s[16:17], vcc, exec
	s_cselect_b32 s13, s15, s19
	s_cselect_b32 s47, s14, s18
	s_ashr_i32 s11, s10, 31
	s_lshl_b64 s[16:17], s[10:11], 19
	s_add_u32 s16, s25, s16
	s_addc_u32 s17, s26, s17
	s_and_b64 s[22:23], vcc, exec
	s_cselect_b32 s11, s17, s21
	s_cselect_b32 s48, s16, s20
	s_add_u32 s18, s18, 0x40080
	s_addc_u32 s19, s19, 0
	s_add_u32 s49, s20, 0x100
	v_mov_b32_e32 v2, 0
	s_addc_u32 s50, s21, 0
	s_mov_b32 s51, -2
	v_mov_b32_e32 v3, v2
	v_mov_b32_e32 v4, v2
	v_mov_b32_e32 v5, v2
	v_mov_b32_e32 v6, v2
	v_mov_b32_e32 v7, v2
	v_mov_b32_e32 v8, v2
	v_mov_b32_e32 v9, v2
	v_mov_b32_e32 v18, v2
	v_mov_b32_e32 v19, v2
	v_mov_b32_e32 v20, v2
	v_mov_b32_e32 v21, v2
	v_mov_b32_e32 v22, v2
	v_mov_b32_e32 v23, v2
	v_mov_b32_e32 v24, v2
	v_mov_b32_e32 v25, v2
	v_mov_b32_e32 v34, v2
	v_mov_b32_e32 v35, v2
	v_mov_b32_e32 v36, v2
	v_mov_b32_e32 v37, v2
	v_mov_b32_e32 v38, v2
	v_mov_b32_e32 v39, v2
	v_mov_b32_e32 v40, v2
	v_mov_b32_e32 v41, v2
	v_mov_b32_e32 v50, v2
	v_mov_b32_e32 v51, v2
	v_mov_b32_e32 v52, v2
	v_mov_b32_e32 v53, v2
	v_mov_b32_e32 v54, v2
	v_mov_b32_e32 v55, v2
	v_mov_b32_e32 v56, v2
	v_mov_b32_e32 v57, v2
	v_mov_b32_e32 v10, v2
	v_mov_b32_e32 v11, v2
	v_mov_b32_e32 v12, v2
	v_mov_b32_e32 v13, v2
	v_mov_b32_e32 v14, v2
	v_mov_b32_e32 v15, v2
	v_mov_b32_e32 v16, v2
	v_mov_b32_e32 v17, v2
	v_mov_b32_e32 v26, v2
	v_mov_b32_e32 v27, v2
	v_mov_b32_e32 v28, v2
	v_mov_b32_e32 v29, v2
	v_mov_b32_e32 v30, v2
	v_mov_b32_e32 v31, v2
	v_mov_b32_e32 v32, v2
	v_mov_b32_e32 v33, v2
	v_mov_b32_e32 v42, v2
	v_mov_b32_e32 v43, v2
	v_mov_b32_e32 v44, v2
	v_mov_b32_e32 v45, v2
	v_mov_b32_e32 v46, v2
	v_mov_b32_e32 v47, v2
	v_mov_b32_e32 v48, v2
	v_mov_b32_e32 v49, v2
	v_mov_b32_e32 v58, v2
	v_mov_b32_e32 v59, v2
	v_mov_b32_e32 v60, v2
	v_mov_b32_e32 v61, v2
	v_mov_b32_e32 v62, v2
	v_mov_b32_e32 v63, v2
	v_mov_b32_e32 v64, v2
	v_mov_b32_e32 v65, v2
	v_mov_b32_e32 v66, v2
	v_mov_b32_e32 v67, v2
	v_mov_b32_e32 v68, v2
	v_mov_b32_e32 v69, v2
	v_mov_b32_e32 v70, v2
	v_mov_b32_e32 v71, v2
	v_mov_b32_e32 v72, v2
	v_mov_b32_e32 v73, v2
	v_mov_b32_e32 v82, v2
	v_mov_b32_e32 v83, v2
	v_mov_b32_e32 v84, v2
	v_mov_b32_e32 v85, v2
	v_mov_b32_e32 v86, v2
	v_mov_b32_e32 v87, v2
	v_mov_b32_e32 v88, v2
	v_mov_b32_e32 v89, v2
	v_mov_b32_e32 v98, v2
	v_mov_b32_e32 v99, v2
	v_mov_b32_e32 v100, v2
	v_mov_b32_e32 v101, v2
	v_mov_b32_e32 v102, v2
	v_mov_b32_e32 v103, v2
	v_mov_b32_e32 v104, v2
	v_mov_b32_e32 v105, v2
	v_mov_b32_e32 v114, v2
	v_mov_b32_e32 v115, v2
	v_mov_b32_e32 v116, v2
	v_mov_b32_e32 v117, v2
	v_mov_b32_e32 v118, v2
	v_mov_b32_e32 v119, v2
	v_mov_b32_e32 v120, v2
	v_mov_b32_e32 v121, v2
	v_mov_b32_e32 v74, v2
	v_mov_b32_e32 v75, v2
	v_mov_b32_e32 v76, v2
	v_mov_b32_e32 v77, v2
	v_mov_b32_e32 v78, v2
	v_mov_b32_e32 v79, v2
	v_mov_b32_e32 v80, v2
	v_mov_b32_e32 v81, v2
	v_mov_b32_e32 v90, v2
	v_mov_b32_e32 v91, v2
	v_mov_b32_e32 v92, v2
	v_mov_b32_e32 v93, v2
	v_mov_b32_e32 v94, v2
	v_mov_b32_e32 v95, v2
	v_mov_b32_e32 v96, v2
	v_mov_b32_e32 v97, v2
	v_mov_b32_e32 v106, v2
	v_mov_b32_e32 v107, v2
	v_mov_b32_e32 v108, v2
	v_mov_b32_e32 v109, v2
	v_mov_b32_e32 v110, v2
	v_mov_b32_e32 v111, v2
	v_mov_b32_e32 v112, v2
	v_mov_b32_e32 v113, v2
	v_mov_b32_e32 v122, v2
	v_mov_b32_e32 v123, v2
	v_mov_b32_e32 v124, v2
	v_mov_b32_e32 v125, v2
	v_mov_b32_e32 v126, v2
	v_mov_b32_e32 v127, v2
	v_mov_b32_e32 v128, v2
	v_mov_b32_e32 v129, v2
	v_or_b32_e32 v159, 0x10000, v140
	v_add_u32_e32 v164, 0x10400, v140
	ds_read_b128 v[160:163], v159
	ds_read_b128 v[164:167], v164
	v_add_u32_e32 v159, 0x10800, v140
	v_add_u32_e32 v172, 0x10c00, v140
	ds_read_b128 v[168:171], v159
	ds_read_b128 v[172:175], v172
.LBB0_2473:
	s_add_u32 s20, s18, 0xfffc0080
	s_addc_u32 s21, s19, -1
	s_cmp_eq_u32 s51, 12
	s_cselect_b32 s23, s13, s21
	s_cselect_b32 s22, s47, s20
	s_cselect_b32 s21, s11, s50
	s_cselect_b32 s20, s48, s49
	v_lshl_add_u64 v[188:189], s[18:19], 0, v[134:135]
	s_add_i32 m0, s27, 0xc000
	ds_read_b128 v[176:179], v139
	ds_read_b128 v[180:183], v139 offset:1024
	ds_read_b128 v[184:187], v139 offset:2048
	ds_read_b128 v[202:205], v139 offset:3072
	ds_read_b128 v[206:209], v139 offset:4096
	ds_read_b128 v[210:213], v139 offset:5120
	ds_read_b128 v[214:217], v139 offset:6144
	ds_read_b128 v[218:221], v139 offset:7168
	global_load_lds_dwordx4 v[188:189], off
	v_lshl_add_u64 v[188:189], s[18:19], 0, v[136:137]
	s_add_i32 m0, s27, 0xe000
	s_nop 0
	global_load_lds_dwordx4 v[188:189], off
	s_waitcnt lgkmcnt(8)
	s_barrier
	s_waitcnt lgkmcnt(0)
	s_setprio 1
	s_waitcnt lgkmcnt(0)
	v_mfma_f32_16x16x32_f16 v[126:129], v[160:163], v[176:179], v[126:129]
	v_mfma_f32_16x16x32_f16 v[122:125], v[168:171], v[176:179], v[122:125]
	v_mfma_f32_16x16x32_f16 v[110:113], v[160:163], v[184:187], v[110:113]
	v_mfma_f32_16x16x32_f16 v[106:109], v[168:171], v[184:187], v[106:109]
	v_mfma_f32_16x16x32_f16 v[94:97], v[160:163], v[206:209], v[94:97]
	v_mfma_f32_16x16x32_f16 v[90:93], v[168:171], v[206:209], v[90:93]
	v_mfma_f32_16x16x32_f16 v[78:81], v[160:163], v[214:217], v[78:81]
	v_mfma_f32_16x16x32_f16 v[74:77], v[168:171], v[214:217], v[74:77]
	v_mfma_f32_16x16x32_f16 v[126:129], v[164:167], v[180:183], v[126:129]
	v_mfma_f32_16x16x32_f16 v[122:125], v[172:175], v[180:183], v[122:125]
	v_mfma_f32_16x16x32_f16 v[110:113], v[164:167], v[202:205], v[110:113]
	v_mfma_f32_16x16x32_f16 v[106:109], v[172:175], v[202:205], v[106:109]
	v_mfma_f32_16x16x32_f16 v[94:97], v[164:167], v[210:213], v[94:97]
	v_mfma_f32_16x16x32_f16 v[90:93], v[172:175], v[210:213], v[90:93]
	v_mfma_f32_16x16x32_f16 v[78:81], v[164:167], v[218:221], v[78:81]
	v_mfma_f32_16x16x32_f16 v[74:77], v[172:175], v[218:221], v[74:77]
	s_setprio 0
	s_barrier
; #define G8_STAGE(bufoff, gbase) do { _Pragma("unroll") for (int _i = 0; _i < 2; ++_i) \
;     __builtin_amdgcn_global_load_lds((const unsigned*)((const char*)(gbase) + voffA[_i]), (LAS unsigned*)(lds + (bufoff) + ldsw + _i * 8192), 16, 0, 0); } while (0)
; #define G8_LDA(dst, b, h) do { _Pragma("unroll") for (int m = 0; m < 4; ++m) _Pragma("unroll") for (int k = 0; k < 2; ++k) dst[m][k] = *(const LAS h16x8*)(lds + G8_SA(b, h) + aoff + m * 2048 + k * 1024); } while (0)
; #define G8_LDB(dst, b, h) do { _Pragma("unroll") for (int n = 0; n < 2; ++n) _Pragma("unroll") for (int k = 0; k < 2; ++k) dst[n][k] = *(const LAS h16x8*)(lds + G8_SB(b, h) + boff + n * 2048 + k * 1024); } while (0)
; #define G8_MMA(ai, bj, At, Bt_) do { __builtin_amdgcn_s_setprio(1); _Pragma("unroll") for (int m = 0; m < 4; ++m) _Pragma("unroll") for (int n = 0; n < 2; ++n) _Pragma("unroll") for (int k = 0; k < 2; ++k) \
;     acc[ai][bj][m][n] = __builtin_amdgcn_mfma_f32_16x16x32_f16(Bt_[n][k], At[m][k], acc[ai][bj][m][n], 0, 0, 0); __builtin_amdgcn_s_setprio(0); } while (0)
; #define G8_WAIT_V(n) asm volatile("s_waitcnt vmcnt(" #n ")" ::: "memory")
; #define G8_WAIT_L(n) asm volatile("s_waitcnt lgkmcnt(" #n ")" ::: "memory")
; #define G8_BAR __builtin_amdgcn_s_barrier()
; #define G8_SCHED __builtin_amdgcn_sched_barrier(0)
; template <class Epi>
; __device__ __forceinline__ void gemm_phase(LAS unsigned char* lds, const h16* A, const h16* Bt, int K, const Order& S, const Epi& E) {
;     ...
;       G8_LDB(B1, 0, 1); G8_STAGE(G8_SB(0, 0), b2);
;       G8_BAR; G8_WAIT_L(0); G8_MMA(0, 1, At, B1); G8_BAR;
;       G8_LDA(At, 0, 1); G8_STAGE(G8_SA(0, 0), a2);
;       G8_BAR; G8_WAIT_L(0); G8_MMA(1, 0, At, B0); G8_BAR; G8_SCHED;
;       G8_STAGE(G8_SB(0, 1), b2 + hstep);
;       G8_WAIT_V(6); G8_BAR; G8_MMA(1, 1, At, B1); G8_BAR;
;       G8_LDB(B0, 1, 0); G8_SCHED; G8_LDA(At, 1, 0); G8_STAGE(G8_SA(0, 1), a2 + hstep);
;       G8_WAIT_L(8); G8_BAR; G8_WAIT_L(0); G8_MMA(0, 0, At, B0); G8_BAR; G8_SCHED;
	v_or_b32_e32 v159, 0x14000, v140
	v_add_u32_e32 v188, 0x14400, v140
	ds_read_b128 v[222:225], v159
	ds_read_b128 v[226:229], v188
	v_add_u32_e32 v159, 0x14800, v140
	v_add_u32_e32 v188, 0x14c00, v140
	s_mov_b32 m0, s28
	ds_read_b128 v[230:233], v159
	ds_read_b128 v[234:237], v188
	v_lshl_add_u64 v[188:189], s[20:21], 0, v[132:133]
	global_load_lds_dwordx4 v[188:189], off
	v_lshl_add_u64 v[238:239], s[20:21], 0, v[130:131]
	s_mov_b32 m0, s29
	s_nop 0
	global_load_lds_dwordx4 v[238:239], off
	s_barrier
	s_waitcnt lgkmcnt(0)
	s_setprio 1
	s_waitcnt lgkmcnt(0)
	v_mfma_f32_16x16x32_f16 v[118:121], v[222:225], v[176:179], v[118:121]
	v_mfma_f32_16x16x32_f16 v[114:117], v[230:233], v[176:179], v[114:117]
	v_mfma_f32_16x16x32_f16 v[102:105], v[222:225], v[184:187], v[102:105]
	v_mfma_f32_16x16x32_f16 v[98:101], v[230:233], v[184:187], v[98:101]
	v_mfma_f32_16x16x32_f16 v[86:89], v[222:225], v[206:209], v[86:89]
	v_mfma_f32_16x16x32_f16 v[82:85], v[230:233], v[206:209], v[82:85]
	v_mfma_f32_16x16x32_f16 v[70:73], v[222:225], v[214:217], v[70:73]
	v_mfma_f32_16x16x32_f16 v[66:69], v[230:233], v[214:217], v[66:69]
	v_mfma_f32_16x16x32_f16 v[118:121], v[226:229], v[180:183], v[118:121]
	v_mfma_f32_16x16x32_f16 v[114:117], v[234:237], v[180:183], v[114:117]
	v_mfma_f32_16x16x32_f16 v[102:105], v[226:229], v[202:205], v[102:105]
	v_mfma_f32_16x16x32_f16 v[98:101], v[234:237], v[202:205], v[98:101]
	v_mfma_f32_16x16x32_f16 v[86:89], v[226:229], v[210:213], v[86:89]
	v_mfma_f32_16x16x32_f16 v[82:85], v[234:237], v[210:213], v[82:85]
	v_mfma_f32_16x16x32_f16 v[70:73], v[226:229], v[218:221], v[70:73]
	v_mfma_f32_16x16x32_f16 v[66:69], v[234:237], v[218:221], v[66:69]
	s_setprio 0
	s_mov_b32 m0, s27
	v_lshl_add_u64 v[240:241], s[22:23], 0, v[132:133]
	s_barrier
	ds_read_b128 v[176:179], v139 offset:16384
	ds_read_b128 v[180:183], v139 offset:17408
	ds_read_b128 v[184:187], v139 offset:18432
	ds_read_b128 v[202:205], v139 offset:19456
	ds_read_b128 v[206:209], v139 offset:20480
	ds_read_b128 v[210:213], v139 offset:21504
	ds_read_b128 v[214:217], v139 offset:22528
	ds_read_b128 v[218:221], v139 offset:23552
	global_load_lds_dwordx4 v[240:241], off
	v_lshl_add_u64 v[242:243], s[22:23], 0, v[130:131]
	s_mov_b32 m0, s30
	s_nop 0
	global_load_lds_dwordx4 v[242:243], off
	s_waitcnt vmcnt(10)
	s_barrier
	s_waitcnt lgkmcnt(0)
	s_setprio 1
	s_waitcnt lgkmcnt(0)
	v_mfma_f32_16x16x32_f16 v[62:65], v[160:163], v[176:179], v[62:65]
	v_mfma_f32_16x16x32_f16 v[58:61], v[168:171], v[176:179], v[58:61]
	v_mfma_f32_16x16x32_f16 v[46:49], v[160:163], v[184:187], v[46:49]
	v_mfma_f32_16x16x32_f16 v[42:45], v[168:171], v[184:187], v[42:45]
	v_mfma_f32_16x16x32_f16 v[30:33], v[160:163], v[206:209], v[30:33]
	v_mfma_f32_16x16x32_f16 v[26:29], v[168:171], v[206:209], v[26:29]
	v_mfma_f32_16x16x32_f16 v[14:17], v[160:163], v[214:217], v[14:17]
	v_mfma_f32_16x16x32_f16 v[10:13], v[168:171], v[214:217], v[10:13]
	v_mfma_f32_16x16x32_f16 v[62:65], v[164:167], v[180:183], v[62:65]
	v_mfma_f32_16x16x32_f16 v[58:61], v[172:175], v[180:183], v[58:61]
	v_mfma_f32_16x16x32_f16 v[46:49], v[164:167], v[202:205], v[46:49]
	v_mfma_f32_16x16x32_f16 v[42:45], v[172:175], v[202:205], v[42:45]
	v_mfma_f32_16x16x32_f16 v[30:33], v[164:167], v[210:213], v[30:33]
	v_mfma_f32_16x16x32_f16 v[26:29], v[172:175], v[210:213], v[26:29]
	v_mfma_f32_16x16x32_f16 v[14:17], v[164:167], v[218:221], v[14:17]
	v_mfma_f32_16x16x32_f16 v[10:13], v[172:175], v[218:221], v[10:13]
	s_setprio 0
	s_barrier
	s_add_u32 s52, s20, 0x40000
	s_addc_u32 s53, s21, 0
	s_mov_b32 m0, s31
	v_lshl_add_u64 v[160:161], s[52:53], 0, v[132:133]
	global_load_lds_dwordx4 v[160:161], off
	v_lshl_add_u64 v[160:161], s[52:53], 0, v[130:131]
	s_mov_b32 m0, s34
	s_nop 0
	global_load_lds_dwordx4 v[160:161], off
	v_or_b32_e32 v159, 0x18000, v140
	v_add_u32_e32 v164, 0x18400, v140
	ds_read_b128 v[160:163], v159
	ds_read_b128 v[164:167], v164
	v_add_u32_e32 v159, 0x18800, v140
	v_add_u32_e32 v172, 0x18c00, v140
	ds_read_b128 v[168:171], v159
	ds_read_b128 v[172:175], v172
	s_waitcnt vmcnt(6)
	s_barrier
	s_setprio 1
	v_mfma_f32_16x16x32_f16 v[54:57], v[222:225], v[176:179], v[54:57]
	v_mfma_f32_16x16x32_f16 v[50:53], v[230:233], v[176:179], v[50:53]
	v_mfma_f32_16x16x32_f16 v[38:41], v[222:225], v[184:187], v[38:41]
	v_mfma_f32_16x16x32_f16 v[34:37], v[230:233], v[184:187], v[34:37]
	v_mfma_f32_16x16x32_f16 v[22:25], v[222:225], v[206:209], v[22:25]
	v_mfma_f32_16x16x32_f16 v[18:21], v[230:233], v[206:209], v[18:21]
	v_mfma_f32_16x16x32_f16 v[6:9], v[222:225], v[214:217], v[6:9]
	v_mfma_f32_16x16x32_f16 v[2:5], v[230:233], v[214:217], v[2:5]
	v_mfma_f32_16x16x32_f16 v[54:57], v[226:229], v[180:183], v[54:57]
	v_mfma_f32_16x16x32_f16 v[50:53], v[234:237], v[180:183], v[50:53]
	v_mfma_f32_16x16x32_f16 v[38:41], v[226:229], v[202:205], v[38:41]
	v_mfma_f32_16x16x32_f16 v[34:37], v[234:237], v[202:205], v[34:37]
	v_mfma_f32_16x16x32_f16 v[22:25], v[226:229], v[210:213], v[22:25]
	v_mfma_f32_16x16x32_f16 v[18:21], v[234:237], v[210:213], v[18:21]
	v_mfma_f32_16x16x32_f16 v[6:9], v[226:229], v[218:221], v[6:9]
	v_mfma_f32_16x16x32_f16 v[2:5], v[234:237], v[218:221], v[2:5]
	s_setprio 0
	s_barrier
	s_add_u32 s22, s22, 0x40000
	s_addc_u32 s23, s23, 0
	s_mov_b32 m0, s35
	v_lshl_add_u64 v[222:223], s[22:23], 0, v[132:133]
	ds_read_b128 v[176:179], v139 offset:32768
	ds_read_b128 v[180:183], v139 offset:33792
	ds_read_b128 v[184:187], v139 offset:34816
	ds_read_b128 v[202:205], v139 offset:35840
	ds_read_b128 v[206:209], v139 offset:36864
	ds_read_b128 v[210:213], v139 offset:37888
	ds_read_b128 v[214:217], v139 offset:38912
	ds_read_b128 v[218:221], v139 offset:39936
	global_load_lds_dwordx4 v[222:223], off
	v_lshl_add_u64 v[222:223], s[22:23], 0, v[130:131]
	s_mov_b32 m0, s36
	s_nop 0
	global_load_lds_dwordx4 v[222:223], off
	s_waitcnt lgkmcnt(8)
	s_barrier
; #define G8_STAGE(bufoff, gbase) do { _Pragma("unroll") for (int _i = 0; _i < 2; ++_i) \
;     __builtin_amdgcn_global_load_lds((const unsigned*)((const char*)(gbase) + voffA[_i]), (LAS unsigned*)(lds + (bufoff) + ldsw + _i * 8192), 16, 0, 0); } while (0)
; #define G8_LDA(dst, b, h) do { _Pragma("unroll") for (int m = 0; m < 4; ++m) _Pragma("unroll") for (int k = 0; k < 2; ++k) dst[m][k] = *(const LAS h16x8*)(lds + G8_SA(b, h) + aoff + m * 2048 + k * 1024); } while (0)
; #define G8_LDB(dst, b, h) do { _Pragma("unroll") for (int n = 0; n < 2; ++n) _Pragma("unroll") for (int k = 0; k < 2; ++k) dst[n][k] = *(const LAS h16x8*)(lds + G8_SB(b, h) + boff + n * 2048 + k * 1024); } while (0)
; #define G8_MMA(ai, bj, At, Bt_) do { __builtin_amdgcn_s_setprio(1); _Pragma("unroll") for (int m = 0; m < 4; ++m) _Pragma("unroll") for (int n = 0; n < 2; ++n) _Pragma("unroll") for (int k = 0; k < 2; ++k) \
;     acc[ai][bj][m][n] = __builtin_amdgcn_mfma_f32_16x16x32_f16(Bt_[n][k], At[m][k], acc[ai][bj][m][n], 0, 0, 0); __builtin_amdgcn_s_setprio(0); } while (0)
; #define G8_WAIT_V(n) asm volatile("s_waitcnt vmcnt(" #n ")" ::: "memory")
; #define G8_WAIT_L(n) asm volatile("s_waitcnt lgkmcnt(" #n ")" ::: "memory")
; #define G8_BAR __builtin_amdgcn_s_barrier()
; #define G8_SCHED __builtin_amdgcn_sched_barrier(0)
; template <class Epi>
; __device__ __forceinline__ void gemm_phase(LAS unsigned char* lds, const h16* A, const h16* Bt, int K, const Order& S, const Epi& E) {
;     ...
;       G8_WAIT_L(8); G8_BAR; G8_WAIT_L(0); G8_MMA(0, 0, At, B0); G8_BAR; G8_SCHED;
;       G8_LDB(B1, 1, 1); G8_STAGE(G8_SB(1, 0), b3);
;       G8_BAR; G8_WAIT_L(0); G8_MMA(0, 1, At, B1); G8_BAR;
;       G8_LDA(At, 1, 1); G8_STAGE(G8_SA(1, 0), a3);
;       G8_BAR; G8_WAIT_L(0); G8_MMA(1, 0, At, B0); G8_BAR; G8_SCHED;
;       G8_STAGE(G8_SB(1, 1), b3 + hstep);
;       G8_WAIT_V(6); G8_BAR; G8_MMA(1, 1, At, B1); G8_BAR;
	s_waitcnt lgkmcnt(0)
	s_setprio 1
	s_waitcnt lgkmcnt(0)
	v_mfma_f32_16x16x32_f16 v[126:129], v[160:163], v[176:179], v[126:129]
	v_mfma_f32_16x16x32_f16 v[122:125], v[168:171], v[176:179], v[122:125]
	v_mfma_f32_16x16x32_f16 v[110:113], v[160:163], v[184:187], v[110:113]
	v_mfma_f32_16x16x32_f16 v[106:109], v[168:171], v[184:187], v[106:109]
	v_mfma_f32_16x16x32_f16 v[94:97], v[160:163], v[206:209], v[94:97]
	v_mfma_f32_16x16x32_f16 v[90:93], v[168:171], v[206:209], v[90:93]
	v_mfma_f32_16x16x32_f16 v[78:81], v[160:163], v[214:217], v[78:81]
	v_mfma_f32_16x16x32_f16 v[74:77], v[168:171], v[214:217], v[74:77]
	v_mfma_f32_16x16x32_f16 v[126:129], v[164:167], v[180:183], v[126:129]
	v_mfma_f32_16x16x32_f16 v[122:125], v[172:175], v[180:183], v[122:125]
	v_mfma_f32_16x16x32_f16 v[110:113], v[164:167], v[202:205], v[110:113]
	v_mfma_f32_16x16x32_f16 v[106:109], v[172:175], v[202:205], v[106:109]
	v_mfma_f32_16x16x32_f16 v[94:97], v[164:167], v[210:213], v[94:97]
	v_mfma_f32_16x16x32_f16 v[90:93], v[172:175], v[210:213], v[90:93]
	v_mfma_f32_16x16x32_f16 v[78:81], v[164:167], v[218:221], v[78:81]
	v_mfma_f32_16x16x32_f16 v[74:77], v[172:175], v[218:221], v[74:77]
	s_setprio 0
	s_barrier
	v_or_b32_e32 v159, 0x1c000, v140
	s_mov_b32 m0, s37
	v_add_u32_e32 v195, 0x1c400, v140
	ds_read_b128 v[222:225], v159
	ds_read_b128 v[226:229], v195
	v_add_u32_e32 v159, 0x1c800, v140
	v_lshl_add_u64 v[188:189], v[188:189], 0, s[94:95]
	v_add_u32_e32 v195, 0x1cc00, v140
	ds_read_b128 v[230:233], v159
	ds_read_b128 v[234:237], v195
	global_load_lds_dwordx4 v[188:189], off
	v_lshl_add_u64 v[188:189], v[238:239], 0, s[94:95]
	s_mov_b32 m0, s38
	s_nop 0
	global_load_lds_dwordx4 v[188:189], off
	s_barrier
	s_waitcnt lgkmcnt(0)
	s_setprio 1
	s_waitcnt lgkmcnt(0)
	v_mfma_f32_16x16x32_f16 v[118:121], v[222:225], v[176:179], v[118:121]
	v_mfma_f32_16x16x32_f16 v[114:117], v[230:233], v[176:179], v[114:117]
	v_mfma_f32_16x16x32_f16 v[102:105], v[222:225], v[184:187], v[102:105]
	v_mfma_f32_16x16x32_f16 v[98:101], v[230:233], v[184:187], v[98:101]
	v_mfma_f32_16x16x32_f16 v[86:89], v[222:225], v[206:209], v[86:89]
	v_mfma_f32_16x16x32_f16 v[82:85], v[230:233], v[206:209], v[82:85]
	v_mfma_f32_16x16x32_f16 v[70:73], v[222:225], v[214:217], v[70:73]
	v_mfma_f32_16x16x32_f16 v[66:69], v[230:233], v[214:217], v[66:69]
	v_mfma_f32_16x16x32_f16 v[118:121], v[226:229], v[180:183], v[118:121]
	v_mfma_f32_16x16x32_f16 v[114:117], v[234:237], v[180:183], v[114:117]
	v_mfma_f32_16x16x32_f16 v[102:105], v[226:229], v[202:205], v[102:105]
	v_mfma_f32_16x16x32_f16 v[98:101], v[234:237], v[202:205], v[98:101]
	v_mfma_f32_16x16x32_f16 v[86:89], v[226:229], v[210:213], v[86:89]
	v_mfma_f32_16x16x32_f16 v[82:85], v[234:237], v[210:213], v[82:85]
	v_mfma_f32_16x16x32_f16 v[70:73], v[226:229], v[218:221], v[70:73]
	v_mfma_f32_16x16x32_f16 v[66:69], v[234:237], v[218:221], v[66:69]
	s_setprio 0
	s_mov_b32 m0, s39
	v_lshl_add_u64 v[188:189], v[240:241], 0, s[94:95]
	s_barrier
	ds_read_b128 v[176:179], v139 offset:49152
	ds_read_b128 v[180:183], v139 offset:50176
	ds_read_b128 v[184:187], v139 offset:51200
	ds_read_b128 v[202:205], v139 offset:52224
	ds_read_b128 v[206:209], v139 offset:53248
	ds_read_b128 v[210:213], v139 offset:54272
	ds_read_b128 v[214:217], v139 offset:55296
	ds_read_b128 v[218:221], v139 offset:56320
	global_load_lds_dwordx4 v[188:189], off
	v_lshl_add_u64 v[188:189], v[242:243], 0, s[94:95]
	s_mov_b32 m0, s40
	s_nop 0
	global_load_lds_dwordx4 v[188:189], off
	s_waitcnt vmcnt(10)
	s_barrier
	s_waitcnt lgkmcnt(0)
	s_setprio 1
	s_waitcnt lgkmcnt(0)
	v_mfma_f32_16x16x32_f16 v[62:65], v[160:163], v[176:179], v[62:65]
	v_mfma_f32_16x16x32_f16 v[58:61], v[168:171], v[176:179], v[58:61]
	v_mfma_f32_16x16x32_f16 v[46:49], v[160:163], v[184:187], v[46:49]
	v_mfma_f32_16x16x32_f16 v[42:45], v[168:171], v[184:187], v[42:45]
	v_mfma_f32_16x16x32_f16 v[30:33], v[160:163], v[206:209], v[30:33]
	v_mfma_f32_16x16x32_f16 v[26:29], v[168:171], v[206:209], v[26:29]
	v_mfma_f32_16x16x32_f16 v[14:17], v[160:163], v[214:217], v[14:17]
	v_mfma_f32_16x16x32_f16 v[10:13], v[168:171], v[214:217], v[10:13]
	v_mfma_f32_16x16x32_f16 v[62:65], v[164:167], v[180:183], v[62:65]
	v_mfma_f32_16x16x32_f16 v[58:61], v[172:175], v[180:183], v[58:61]
	v_mfma_f32_16x16x32_f16 v[46:49], v[164:167], v[202:205], v[46:49]
	v_mfma_f32_16x16x32_f16 v[42:45], v[172:175], v[202:205], v[42:45]
	v_mfma_f32_16x16x32_f16 v[30:33], v[164:167], v[210:213], v[30:33]
	v_mfma_f32_16x16x32_f16 v[26:29], v[172:175], v[210:213], v[26:29]
	v_mfma_f32_16x16x32_f16 v[14:17], v[164:167], v[218:221], v[14:17]
	v_mfma_f32_16x16x32_f16 v[10:13], v[172:175], v[218:221], v[10:13]
	s_setprio 0
	s_barrier
	s_add_u32 s20, s20, 0x40080
	s_addc_u32 s21, s21, 0
	s_mov_b32 m0, s41
	v_lshl_add_u64 v[160:161], s[20:21], 0, v[132:133]
	global_load_lds_dwordx4 v[160:161], off
	v_lshl_add_u64 v[160:161], s[20:21], 0, v[130:131]
	s_mov_b32 m0, s42
	s_nop 0
	global_load_lds_dwordx4 v[160:161], off
	v_or_b32_e32 v159, 0x10000, v140
	v_add_u32_e32 v164, 0x10400, v140
	ds_read_b128 v[160:163], v159
	ds_read_b128 v[164:167], v164
	v_add_u32_e32 v159, 0x10800, v140
	v_add_u32_e32 v172, 0x10c00, v140
	ds_read_b128 v[168:171], v159
	ds_read_b128 v[172:175], v172
	s_waitcnt vmcnt(6)
	s_barrier
; #define G8_MMA(ai, bj, At, Bt_) do { __builtin_amdgcn_s_setprio(1); _Pragma("unroll") for (int m = 0; m < 4; ++m) _Pragma("unroll") for (int n = 0; n < 2; ++n) _Pragma("unroll") for (int k = 0; k < 2; ++k) \
;     acc[ai][bj][m][n] = __builtin_amdgcn_mfma_f32_16x16x32_f16(Bt_[n][k], At[m][k], acc[ai][bj][m][n], 0, 0, 0); __builtin_amdgcn_s_setprio(0); } while (0)
; #define G8_WAIT_V(n) asm volatile("s_waitcnt vmcnt(" #n ")" ::: "memory")
; #define G8_BAR __builtin_amdgcn_s_barrier()
; template <class Epi>
; __device__ __forceinline__ void gemm_phase(LAS unsigned char* lds, const h16* A, const h16* Bt, int K, const Order& S, const Epi& E) {
;     ...
;       G8_WAIT_V(6); G8_BAR; G8_MMA(1, 1, At, B1); G8_BAR;
;     }
;   __device__ __forceinline__ void operator()(const f32x4 (&acc)[2][2][4][2], const g8::Unit& u, int ui, int wr, int wc, int fr, int fq) const {
; #pragma unroll
;     for (int ai = 0; ai < 2; ++ai)
; #pragma unroll
;       for (int m = 0; m < 4; ++m) {
;         const int rl = 128 * ai + 64 * wr + 16 * m + fr;
;         const float r = rsl[ui * 256 + rl];
;         h16* rowp = hid + (size_t)(u.pm * 256 + rl) * DFF + 256 * u.pn + 32 * wc + 8 * fq;
; #pragma unroll
;         for (int bj = 0; bj < 2; ++bj) {
;           f32x4 v[2];
; #pragma unroll
;           for (int n = 0; n < 2; ++n) {
;             v[n] = acc[ai][bj][m][n] * r;
; #pragma unroll
;             for (int j = 0; j < 4; ++j) { const float t = fmaxf(v[n][j], 0.f); v[n][j] = t * t; }
;           }
;           __builtin_nontemporal_store(pack8(v[0], v[1]), (h16x8*)(rowp + 128 * bj));
;         }
;       }
	s_setprio 1
	v_mfma_f32_16x16x32_f16 v[54:57], v[222:225], v[176:179], v[54:57]
	v_mfma_f32_16x16x32_f16 v[50:53], v[230:233], v[176:179], v[50:53]
	v_mfma_f32_16x16x32_f16 v[38:41], v[222:225], v[184:187], v[38:41]
	v_mfma_f32_16x16x32_f16 v[34:37], v[230:233], v[184:187], v[34:37]
	v_mfma_f32_16x16x32_f16 v[22:25], v[222:225], v[206:209], v[22:25]
	v_mfma_f32_16x16x32_f16 v[18:21], v[230:233], v[206:209], v[18:21]
	v_mfma_f32_16x16x32_f16 v[6:9], v[222:225], v[214:217], v[6:9]
	v_mfma_f32_16x16x32_f16 v[2:5], v[230:233], v[214:217], v[2:5]
	v_mfma_f32_16x16x32_f16 v[54:57], v[226:229], v[180:183], v[54:57]
	v_mfma_f32_16x16x32_f16 v[50:53], v[234:237], v[180:183], v[50:53]
	v_mfma_f32_16x16x32_f16 v[38:41], v[226:229], v[202:205], v[38:41]
	v_mfma_f32_16x16x32_f16 v[34:37], v[234:237], v[202:205], v[34:37]
	v_mfma_f32_16x16x32_f16 v[22:25], v[226:229], v[210:213], v[22:25]
	v_mfma_f32_16x16x32_f16 v[18:21], v[234:237], v[210:213], v[18:21]
	v_mfma_f32_16x16x32_f16 v[6:9], v[226:229], v[218:221], v[6:9]
	v_mfma_f32_16x16x32_f16 v[2:5], v[234:237], v[218:221], v[2:5]
	s_setprio 0
	s_add_i32 s51, s51, 2
	s_add_u32 s18, s18, 0x100
	s_addc_u32 s19, s19, 0
	s_add_u32 s49, s49, 0x100
	s_addc_u32 s50, s50, 0
	s_cmp_gt_u32 s51, 13
	s_barrier
	s_cbranch_scc0 .LBB0_2473
	s_waitcnt lgkmcnt(0)
	v_lshl_add_u32 v159, s44, 10, v158
	s_waitcnt vmcnt(0)
	ds_read2_b32 v[160:161], v159 offset1:16
	s_lshl_b32 s11, s46, 8
	v_add_u32_e32 v162, s11, v138
	s_lshl_b32 s18, s45, 8
	v_ashrrev_i32_e32 v163, 31, v162
	s_waitcnt lgkmcnt(0)
	v_pk_mul_f32 v[128:129], v[128:129], v[160:161] op_sel_hi:[1,0]
	v_pk_mul_f32 v[126:127], v[126:127], v[160:161] op_sel_hi:[1,0]
	v_pk_mul_f32 v[122:123], v[122:123], v[160:161] op_sel_hi:[1,0]
	v_max_f32_e32 v166, 0, v126
	v_max_f32_e32 v126, 0, v127
	v_max_f32_e32 v127, 0, v128
	v_max_f32_e32 v128, 0, v129
	v_pk_mul_f32 v[124:125], v[124:125], v[160:161] op_sel_hi:[1,0]
	v_max_f32_e32 v129, 0, v122
	v_max_f32_e32 v164, 0, v123
	v_pk_mul_f32 v[122:123], v[126:127], v[126:127]
	v_max_f32_e32 v165, 0, v124
	v_fma_mixlo_f16 v124, v166, v166, 0
	v_cvt_pk_f16_f32 v123, v122, v123
	s_ashr_i32 s19, s18, 31
	v_lshlrev_b64 v[162:163], 13, v[162:163]
	v_max_f32_e32 v167, 0, v125
	v_pack_b32_f16 v122, v124, v123
	v_pk_mul_f32 v[124:125], v[128:129], v[128:129]
	v_lshl_add_u64 v[162:163], s[0:1], 0, v[162:163]
	s_lshl_b64 s[18:19], s[18:19], 1
	v_cvt_pk_f16_f32 v126, v124, v125
	v_pk_mul_f32 v[124:125], v[164:165], v[164:165]
	v_lshl_add_u64 v[162:163], v[162:163], 0, s[18:19]
	v_cvt_pk_f16_f32 v125, v124, v125
	v_lshl_add_u64 v[162:163], v[162:163], 0, s[92:93]
	v_alignbit_b32 v124, v125, v126, 16
	v_lshrrev_b32_e32 v125, 16, v125
	v_lshl_add_u64 v[162:163], v[162:163], 0, v[0:1]
	v_alignbit_b32 v123, v126, v123, 16
	v_fma_mixhi_f16 v125, v167, v167, 0
	v_pk_mul_f32 v[120:121], v[120:121], v[160:161] op_sel_hi:[1,0]
	v_pk_mul_f32 v[118:119], v[118:119], v[160:161] op_sel_hi:[1,0]
	global_store_dwordx4 v[162:163], v[122:125], off nt
	v_pk_mul_f32 v[114:115], v[114:115], v[160:161] op_sel_hi:[1,0]
	v_pk_mul_f32 v[116:117], v[116:117], v[160:161] op_sel_hi:[1,0]
	v_max_f32_e32 v124, 0, v118
	v_max_f32_e32 v118, 0, v119
	v_max_f32_e32 v119, 0, v120
	v_max_f32_e32 v120, 0, v121
	v_max_f32_e32 v121, 0, v114
	v_max_f32_e32 v122, 0, v115
	v_pk_mul_f32 v[114:115], v[118:119], v[118:119]
	v_max_f32_e32 v123, 0, v116
	v_fma_mixlo_f16 v116, v124, v124, 0
	v_cvt_pk_f16_f32 v115, v114, v115
	v_max_f32_e32 v125, 0, v117
	v_pack_b32_f16 v114, v116, v115
	v_pk_mul_f32 v[116:117], v[120:121], v[120:121]
	s_and_b64 vcc, exec, s[6:7]
	v_cvt_pk_f16_f32 v118, v116, v117
	v_pk_mul_f32 v[116:117], v[122:123], v[122:123]
	v_alignbit_b32 v115, v118, v115, 16
	v_cvt_pk_f16_f32 v117, v116, v117
	v_alignbit_b32 v116, v117, v118, 16
	v_lshrrev_b32_e32 v117, 16, v117
	v_fma_mixhi_f16 v117, v125, v125, 0
	global_store_dwordx4 v[162:163], v[114:117], off offset:256 nt
	s_mov_b32 s45, s10
	s_mov_b32 s46, s12
	v_mov_b32_e32 v116, v161
	v_pk_mul_f32 v[110:111], v[110:111], v[116:117] op_sel_hi:[1,0]
	v_pk_mul_f32 v[112:113], v[112:113], v[116:117] op_sel_hi:[1,0]
	v_max_f32_e32 v117, 0, v110
	v_max_f32_e32 v110, 0, v111
	v_max_f32_e32 v111, 0, v112
	v_pk_mul_f32 v[106:107], v[106:107], v[116:117] op_sel_hi:[1,0]
	v_add_u32_e32 v114, s11, v141
	v_max_f32_e32 v112, 0, v113
	v_pk_mul_f32 v[108:109], v[108:109], v[116:117] op_sel_hi:[1,0]
	v_max_f32_e32 v113, 0, v106
	v_max_f32_e32 v118, 0, v107
	v_pk_mul_f32 v[106:107], v[110:111], v[110:111]
	v_ashrrev_i32_e32 v115, 31, v114
	v_max_f32_e32 v119, 0, v108
	v_fma_mixlo_f16 v108, v117, v117, 0
	v_cvt_pk_f16_f32 v107, v106, v107
	v_lshlrev_b64 v[114:115], 13, v[114:115]
	v_max_f32_e32 v120, 0, v109
	v_pack_b32_f16 v106, v108, v107
	v_pk_mul_f32 v[108:109], v[112:113], v[112:113]
	v_lshl_add_u64 v[114:115], s[0:1], 0, v[114:115]
	v_cvt_pk_f16_f32 v110, v108, v109
	v_pk_mul_f32 v[108:109], v[118:119], v[118:119]
	v_lshl_add_u64 v[114:115], v[114:115], 0, s[18:19]
	v_cvt_pk_f16_f32 v109, v108, v109
	v_lshl_add_u64 v[114:115], v[114:115], 0, s[92:93]
	v_alignbit_b32 v108, v109, v110, 16
	v_lshrrev_b32_e32 v109, 16, v109
	v_lshl_add_u64 v[114:115], v[114:115], 0, v[0:1]
	v_alignbit_b32 v107, v110, v107, 16
	v_fma_mixhi_f16 v109, v120, v120, 0
	v_pk_mul_f32 v[104:105], v[104:105], v[116:117] op_sel_hi:[1,0]
	v_pk_mul_f32 v[102:103], v[102:103], v[116:117] op_sel_hi:[1,0]
	global_store_dwordx4 v[114:115], v[106:109], off nt
	v_pk_mul_f32 v[98:99], v[98:99], v[116:117] op_sel_hi:[1,0]
	v_pk_mul_f32 v[100:101], v[100:101], v[116:117] op_sel_hi:[1,0]
	v_max_f32_e32 v108, 0, v102
	v_max_f32_e32 v102, 0, v103
	v_max_f32_e32 v103, 0, v104
	v_max_f32_e32 v104, 0, v105
	v_max_f32_e32 v105, 0, v98
	v_max_f32_e32 v106, 0, v99
	v_pk_mul_f32 v[98:99], v[102:103], v[102:103]
	v_max_f32_e32 v107, 0, v100
	v_fma_mixlo_f16 v100, v108, v108, 0
	v_cvt_pk_f16_f32 v99, v98, v99
	v_max_f32_e32 v109, 0, v101
	v_pack_b32_f16 v98, v100, v99
	v_pk_mul_f32 v[100:101], v[104:105], v[104:105]
	s_mov_b64 s[20:21], s[16:17]
	v_cvt_pk_f16_f32 v102, v100, v101
	v_pk_mul_f32 v[100:101], v[106:107], v[106:107]
	v_alignbit_b32 v99, v102, v99, 16
	v_cvt_pk_f16_f32 v101, v100, v101
	v_alignbit_b32 v100, v101, v102, 16
	v_lshrrev_b32_e32 v101, 16, v101
	v_fma_mixhi_f16 v101, v109, v109, 0
	global_store_dwordx4 v[114:115], v[98:101], off offset:256 nt
	ds_read2_b32 v[98:99], v159 offset0:32 offset1:48
	s_mov_b32 s44, s43
	v_add_u32_e32 v100, s11, v152
	v_ashrrev_i32_e32 v101, 31, v100
	v_lshlrev_b64 v[100:101], 13, v[100:101]
	s_waitcnt lgkmcnt(0)
;   __device__ __forceinline__ void operator()(const f32x4 (&acc)[2][2][4][2], const g8::Unit& u, int ui, int wr, int wc, int fr, int fq) const {
; #pragma unroll
;     for (int ai = 0; ai < 2; ++ai)
; #pragma unroll
;       for (int m = 0; m < 4; ++m) {
;         const int rl = 128 * ai + 64 * wr + 16 * m + fr;
;         const float r = rsl[ui * 256 + rl];
;         h16* rowp = hid + (size_t)(u.pm * 256 + rl) * DFF + 256 * u.pn + 32 * wc + 8 * fq;
; #pragma unroll
;         for (int bj = 0; bj < 2; ++bj) {
;           f32x4 v[2];
; #pragma unroll
;           for (int n = 0; n < 2; ++n) {
;             v[n] = acc[ai][bj][m][n] * r;
; #pragma unroll
;             for (int j = 0; j < 4; ++j) { const float t = fmaxf(v[n][j], 0.f); v[n][j] = t * t; }
;           }
;           __builtin_nontemporal_store(pack8(v[0], v[1]), (h16x8*)(rowp + 128 * bj));
;         }
;       }
	v_pk_mul_f32 v[96:97], v[96:97], v[98:99] op_sel_hi:[1,0]
	v_pk_mul_f32 v[94:95], v[94:95], v[98:99] op_sel_hi:[1,0]
	v_pk_mul_f32 v[90:91], v[90:91], v[98:99] op_sel_hi:[1,0]
	v_max_f32_e32 v104, 0, v94
	v_max_f32_e32 v94, 0, v95
	v_max_f32_e32 v95, 0, v96
	v_max_f32_e32 v96, 0, v97
	v_pk_mul_f32 v[92:93], v[92:93], v[98:99] op_sel_hi:[1,0]
	v_max_f32_e32 v97, 0, v90
	v_max_f32_e32 v102, 0, v91
	v_pk_mul_f32 v[90:91], v[94:95], v[94:95]
	v_max_f32_e32 v103, 0, v92
	v_fma_mixlo_f16 v92, v104, v104, 0
	v_cvt_pk_f16_f32 v91, v90, v91
	v_max_f32_e32 v105, 0, v93
	v_pack_b32_f16 v90, v92, v91
	v_pk_mul_f32 v[92:93], v[96:97], v[96:97]
	v_lshl_add_u64 v[100:101], s[0:1], 0, v[100:101]
	v_cvt_pk_f16_f32 v94, v92, v93
	v_pk_mul_f32 v[92:93], v[102:103], v[102:103]
	v_lshl_add_u64 v[100:101], v[100:101], 0, s[18:19]
	v_cvt_pk_f16_f32 v93, v92, v93
	v_lshl_add_u64 v[100:101], v[100:101], 0, s[92:93]
	v_alignbit_b32 v92, v93, v94, 16
	v_lshrrev_b32_e32 v93, 16, v93
	v_lshl_add_u64 v[100:101], v[100:101], 0, v[0:1]
	v_alignbit_b32 v91, v94, v91, 16
	v_fma_mixhi_f16 v93, v105, v105, 0
	v_pk_mul_f32 v[88:89], v[88:89], v[98:99] op_sel_hi:[1,0]
	v_pk_mul_f32 v[86:87], v[86:87], v[98:99] op_sel_hi:[1,0]
	global_store_dwordx4 v[100:101], v[90:93], off nt
	v_pk_mul_f32 v[82:83], v[82:83], v[98:99] op_sel_hi:[1,0]
	v_pk_mul_f32 v[84:85], v[84:85], v[98:99] op_sel_hi:[1,0]
	v_max_f32_e32 v92, 0, v86
	v_max_f32_e32 v86, 0, v87
	v_max_f32_e32 v87, 0, v88
	v_max_f32_e32 v88, 0, v89
	v_max_f32_e32 v89, 0, v82
	v_max_f32_e32 v90, 0, v83
	v_pk_mul_f32 v[82:83], v[86:87], v[86:87]
	v_max_f32_e32 v91, 0, v84
	v_fma_mixlo_f16 v84, v92, v92, 0
	v_cvt_pk_f16_f32 v83, v82, v83
	v_max_f32_e32 v93, 0, v85
	v_pack_b32_f16 v82, v84, v83
	v_pk_mul_f32 v[84:85], v[88:89], v[88:89]
	s_nop 0
	v_cvt_pk_f16_f32 v86, v84, v85
	v_pk_mul_f32 v[84:85], v[90:91], v[90:91]
	v_alignbit_b32 v83, v86, v83, 16
	v_cvt_pk_f16_f32 v85, v84, v85
	v_alignbit_b32 v84, v85, v86, 16
	v_lshrrev_b32_e32 v85, 16, v85
	v_fma_mixhi_f16 v85, v93, v93, 0
	global_store_dwordx4 v[100:101], v[82:85], off offset:256 nt
	s_nop 1
	v_mov_b32_e32 v84, v99
	v_pk_mul_f32 v[78:79], v[78:79], v[84:85] op_sel_hi:[1,0]
	v_pk_mul_f32 v[80:81], v[80:81], v[84:85] op_sel_hi:[1,0]
	v_max_f32_e32 v85, 0, v78
	v_max_f32_e32 v78, 0, v79
	v_max_f32_e32 v79, 0, v80
	v_pk_mul_f32 v[74:75], v[74:75], v[84:85] op_sel_hi:[1,0]
	v_add_u32_e32 v82, s11, v153
	v_max_f32_e32 v80, 0, v81
	v_pk_mul_f32 v[76:77], v[76:77], v[84:85] op_sel_hi:[1,0]
	v_max_f32_e32 v81, 0, v74
	v_max_f32_e32 v86, 0, v75
	v_pk_mul_f32 v[74:75], v[78:79], v[78:79]
	v_ashrrev_i32_e32 v83, 31, v82
	v_max_f32_e32 v87, 0, v76
	v_fma_mixlo_f16 v76, v85, v85, 0
	v_cvt_pk_f16_f32 v75, v74, v75
	v_lshlrev_b64 v[82:83], 13, v[82:83]
	v_max_f32_e32 v88, 0, v77
	v_pack_b32_f16 v74, v76, v75
	v_pk_mul_f32 v[76:77], v[80:81], v[80:81]
	v_lshl_add_u64 v[82:83], s[0:1], 0, v[82:83]
	v_cvt_pk_f16_f32 v78, v76, v77
	v_pk_mul_f32 v[76:77], v[86:87], v[86:87]
	v_lshl_add_u64 v[82:83], v[82:83], 0, s[18:19]
	v_cvt_pk_f16_f32 v77, v76, v77
	v_lshl_add_u64 v[82:83], v[82:83], 0, s[92:93]
	v_alignbit_b32 v76, v77, v78, 16
	v_lshrrev_b32_e32 v77, 16, v77
	v_lshl_add_u64 v[82:83], v[82:83], 0, v[0:1]
	v_alignbit_b32 v75, v78, v75, 16
	v_fma_mixhi_f16 v77, v88, v88, 0
	v_pk_mul_f32 v[72:73], v[72:73], v[84:85] op_sel_hi:[1,0]
	v_pk_mul_f32 v[70:71], v[70:71], v[84:85] op_sel_hi:[1,0]
	global_store_dwordx4 v[82:83], v[74:77], off nt
	v_pk_mul_f32 v[66:67], v[66:67], v[84:85] op_sel_hi:[1,0]
	v_pk_mul_f32 v[68:69], v[68:69], v[84:85] op_sel_hi:[1,0]
	v_max_f32_e32 v76, 0, v70
	v_max_f32_e32 v70, 0, v71
	v_max_f32_e32 v71, 0, v72
	v_max_f32_e32 v72, 0, v73
	v_max_f32_e32 v73, 0, v66
	v_max_f32_e32 v74, 0, v67
	v_pk_mul_f32 v[66:67], v[70:71], v[70:71]
	v_max_f32_e32 v75, 0, v68
	v_fma_mixlo_f16 v68, v76, v76, 0
	v_cvt_pk_f16_f32 v67, v66, v67
	v_max_f32_e32 v77, 0, v69
	v_pack_b32_f16 v66, v68, v67
	v_pk_mul_f32 v[68:69], v[72:73], v[72:73]
	s_nop 0
	v_cvt_pk_f16_f32 v70, v68, v69
	v_pk_mul_f32 v[68:69], v[74:75], v[74:75]
	v_alignbit_b32 v67, v70, v67, 16
	v_cvt_pk_f16_f32 v69, v68, v69
	v_alignbit_b32 v68, v69, v70, 16
	v_lshrrev_b32_e32 v69, 16, v69
	v_fma_mixhi_f16 v69, v77, v77, 0
	global_store_dwordx4 v[82:83], v[66:69], off offset:256 nt
	ds_read2_b32 v[66:67], v159 offset0:128 offset1:144
	s_waitcnt lgkmcnt(0)
;   __device__ __forceinline__ void operator()(const f32x4 (&acc)[2][2][4][2], const g8::Unit& u, int ui, int wr, int wc, int fr, int fq) const {
; #pragma unroll
;     for (int ai = 0; ai < 2; ++ai)
; #pragma unroll
;       for (int m = 0; m < 4; ++m) {
;         const int rl = 128 * ai + 64 * wr + 16 * m + fr;
;         const float r = rsl[ui * 256 + rl];
;         h16* rowp = hid + (size_t)(u.pm * 256 + rl) * DFF + 256 * u.pn + 32 * wc + 8 * fq;
; #pragma unroll
;         for (int bj = 0; bj < 2; ++bj) {
;           f32x4 v[2];
; #pragma unroll
;           for (int n = 0; n < 2; ++n) {
;             v[n] = acc[ai][bj][m][n] * r;
; #pragma unroll
;             for (int j = 0; j < 4; ++j) { const float t = fmaxf(v[n][j], 0.f); v[n][j] = t * t; }
;           }
;           __builtin_nontemporal_store(pack8(v[0], v[1]), (h16x8*)(rowp + 128 * bj));
;         }
;       }
	v_pk_mul_f32 v[64:65], v[64:65], v[66:67] op_sel_hi:[1,0]
	v_pk_mul_f32 v[62:63], v[62:63], v[66:67] op_sel_hi:[1,0]
	v_pk_mul_f32 v[58:59], v[58:59], v[66:67] op_sel_hi:[1,0]
	v_max_f32_e32 v72, 0, v62
	v_max_f32_e32 v62, 0, v63
	v_max_f32_e32 v63, 0, v64
	v_add_u32_e32 v68, s11, v154
	v_max_f32_e32 v64, 0, v65
	v_pk_mul_f32 v[60:61], v[60:61], v[66:67] op_sel_hi:[1,0]
	v_max_f32_e32 v65, 0, v58
	v_max_f32_e32 v70, 0, v59
	v_pk_mul_f32 v[58:59], v[62:63], v[62:63]
	v_ashrrev_i32_e32 v69, 31, v68
	v_max_f32_e32 v71, 0, v60
	v_fma_mixlo_f16 v60, v72, v72, 0
	v_cvt_pk_f16_f32 v59, v58, v59
	v_lshlrev_b64 v[68:69], 13, v[68:69]
	v_max_f32_e32 v73, 0, v61
	v_pack_b32_f16 v58, v60, v59
	v_pk_mul_f32 v[60:61], v[64:65], v[64:65]
	v_lshl_add_u64 v[68:69], s[0:1], 0, v[68:69]
	v_cvt_pk_f16_f32 v62, v60, v61
	v_pk_mul_f32 v[60:61], v[70:71], v[70:71]
	v_lshl_add_u64 v[68:69], v[68:69], 0, s[18:19]
	v_cvt_pk_f16_f32 v61, v60, v61
	v_lshl_add_u64 v[68:69], v[68:69], 0, s[92:93]
	v_alignbit_b32 v60, v61, v62, 16
	v_lshrrev_b32_e32 v61, 16, v61
	v_lshl_add_u64 v[68:69], v[68:69], 0, v[0:1]
	v_alignbit_b32 v59, v62, v59, 16
	v_fma_mixhi_f16 v61, v73, v73, 0
	v_pk_mul_f32 v[56:57], v[56:57], v[66:67] op_sel_hi:[1,0]
	v_pk_mul_f32 v[54:55], v[54:55], v[66:67] op_sel_hi:[1,0]
	global_store_dwordx4 v[68:69], v[58:61], off nt
	v_pk_mul_f32 v[50:51], v[50:51], v[66:67] op_sel_hi:[1,0]
	v_pk_mul_f32 v[52:53], v[52:53], v[66:67] op_sel_hi:[1,0]
	v_max_f32_e32 v60, 0, v54
	v_max_f32_e32 v54, 0, v55
	v_max_f32_e32 v55, 0, v56
	v_max_f32_e32 v56, 0, v57
	v_max_f32_e32 v57, 0, v50
	v_max_f32_e32 v58, 0, v51
	v_pk_mul_f32 v[50:51], v[54:55], v[54:55]
	v_max_f32_e32 v59, 0, v52
	v_fma_mixlo_f16 v52, v60, v60, 0
	v_cvt_pk_f16_f32 v51, v50, v51
	v_max_f32_e32 v61, 0, v53
	v_pack_b32_f16 v50, v52, v51
	v_pk_mul_f32 v[52:53], v[56:57], v[56:57]
	s_nop 0
	v_cvt_pk_f16_f32 v54, v52, v53
	v_pk_mul_f32 v[52:53], v[58:59], v[58:59]
	v_alignbit_b32 v51, v54, v51, 16
	v_cvt_pk_f16_f32 v53, v52, v53
	v_alignbit_b32 v52, v53, v54, 16
	v_lshrrev_b32_e32 v53, 16, v53
	v_fma_mixhi_f16 v53, v61, v61, 0
	global_store_dwordx4 v[68:69], v[50:53], off offset:256 nt
	s_nop 1
	v_mov_b32_e32 v52, v67
	v_pk_mul_f32 v[46:47], v[46:47], v[52:53] op_sel_hi:[1,0]
	v_pk_mul_f32 v[48:49], v[48:49], v[52:53] op_sel_hi:[1,0]
	v_max_f32_e32 v53, 0, v46
	v_max_f32_e32 v46, 0, v47
	v_max_f32_e32 v47, 0, v48
	v_pk_mul_f32 v[42:43], v[42:43], v[52:53] op_sel_hi:[1,0]
	v_add_u32_e32 v50, s11, v155
	v_max_f32_e32 v48, 0, v49
	v_pk_mul_f32 v[44:45], v[44:45], v[52:53] op_sel_hi:[1,0]
	v_max_f32_e32 v49, 0, v42
	v_max_f32_e32 v54, 0, v43
	v_pk_mul_f32 v[42:43], v[46:47], v[46:47]
	v_ashrrev_i32_e32 v51, 31, v50
	v_max_f32_e32 v55, 0, v44
	v_fma_mixlo_f16 v44, v53, v53, 0
	v_cvt_pk_f16_f32 v43, v42, v43
	v_lshlrev_b64 v[50:51], 13, v[50:51]
	v_max_f32_e32 v56, 0, v45
	v_pack_b32_f16 v42, v44, v43
	v_pk_mul_f32 v[44:45], v[48:49], v[48:49]
	v_lshl_add_u64 v[50:51], s[0:1], 0, v[50:51]
	v_cvt_pk_f16_f32 v46, v44, v45
	v_pk_mul_f32 v[44:45], v[54:55], v[54:55]
	v_lshl_add_u64 v[50:51], v[50:51], 0, s[18:19]
	v_cvt_pk_f16_f32 v45, v44, v45
	v_lshl_add_u64 v[50:51], v[50:51], 0, s[92:93]
	v_alignbit_b32 v44, v45, v46, 16
	v_lshrrev_b32_e32 v45, 16, v45
	v_lshl_add_u64 v[50:51], v[50:51], 0, v[0:1]
	v_alignbit_b32 v43, v46, v43, 16
	v_fma_mixhi_f16 v45, v56, v56, 0
	v_pk_mul_f32 v[40:41], v[40:41], v[52:53] op_sel_hi:[1,0]
	v_pk_mul_f32 v[38:39], v[38:39], v[52:53] op_sel_hi:[1,0]
	global_store_dwordx4 v[50:51], v[42:45], off nt
	v_pk_mul_f32 v[34:35], v[34:35], v[52:53] op_sel_hi:[1,0]
	v_pk_mul_f32 v[36:37], v[36:37], v[52:53] op_sel_hi:[1,0]
	v_max_f32_e32 v44, 0, v38
	v_max_f32_e32 v38, 0, v39
	v_max_f32_e32 v39, 0, v40
	v_max_f32_e32 v40, 0, v41
	v_max_f32_e32 v41, 0, v34
	v_max_f32_e32 v42, 0, v35
	v_pk_mul_f32 v[34:35], v[38:39], v[38:39]
	v_max_f32_e32 v43, 0, v36
	v_fma_mixlo_f16 v36, v44, v44, 0
	v_cvt_pk_f16_f32 v35, v34, v35
	v_max_f32_e32 v45, 0, v37
	v_pack_b32_f16 v34, v36, v35
	v_pk_mul_f32 v[36:37], v[40:41], v[40:41]
	s_nop 0
	v_cvt_pk_f16_f32 v38, v36, v37
	v_pk_mul_f32 v[36:37], v[42:43], v[42:43]
	v_alignbit_b32 v35, v38, v35, 16
	v_cvt_pk_f16_f32 v37, v36, v37
	v_alignbit_b32 v36, v37, v38, 16
	v_lshrrev_b32_e32 v37, 16, v37
	v_fma_mixhi_f16 v37, v45, v45, 0
	global_store_dwordx4 v[50:51], v[34:37], off offset:256 nt
	ds_read2_b32 v[34:35], v159 offset0:160 offset1:176
	s_waitcnt lgkmcnt(0)
; #define G8_WAIT_V(n) asm volatile("s_waitcnt vmcnt(" #n ")" ::: "memory")
; #define G8_BAR __builtin_amdgcn_s_barrier()
; template <class Epi>
; __device__ __forceinline__ void gemm_phase(LAS unsigned char* lds, const h16* A, const h16* Bt, int K, const Order& S, const Epi& E) {
;     ...
;   G8_WAIT_V(0);
;   if (wr == 0) G8_BAR;
;   G8_BAR;
;   __device__ __forceinline__ void operator()(const f32x4 (&acc)[2][2][4][2], const g8::Unit& u, int ui, int wr, int wc, int fr, int fq) const {
; #pragma unroll
;     for (int ai = 0; ai < 2; ++ai)
; #pragma unroll
;       for (int m = 0; m < 4; ++m) {
;         const int rl = 128 * ai + 64 * wr + 16 * m + fr;
;         const float r = rsl[ui * 256 + rl];
;         h16* rowp = hid + (size_t)(u.pm * 256 + rl) * DFF + 256 * u.pn + 32 * wc + 8 * fq;
; #pragma unroll
;         for (int bj = 0; bj < 2; ++bj) {
;           f32x4 v[2];
; #pragma unroll
;           for (int n = 0; n < 2; ++n) {
;             v[n] = acc[ai][bj][m][n] * r;
; #pragma unroll
;             for (int j = 0; j < 4; ++j) { const float t = fmaxf(v[n][j], 0.f); v[n][j] = t * t; }
;           }
;           __builtin_nontemporal_store(pack8(v[0], v[1]), (h16x8*)(rowp + 128 * bj));
;         }
;       }
	v_pk_mul_f32 v[32:33], v[32:33], v[34:35] op_sel_hi:[1,0]
	v_pk_mul_f32 v[30:31], v[30:31], v[34:35] op_sel_hi:[1,0]
	v_pk_mul_f32 v[26:27], v[26:27], v[34:35] op_sel_hi:[1,0]
	v_max_f32_e32 v40, 0, v30
	v_max_f32_e32 v30, 0, v31
	v_max_f32_e32 v31, 0, v32
	v_add_u32_e32 v36, s11, v156
	v_max_f32_e32 v32, 0, v33
	v_pk_mul_f32 v[28:29], v[28:29], v[34:35] op_sel_hi:[1,0]
	v_max_f32_e32 v33, 0, v26
	v_max_f32_e32 v38, 0, v27
	v_pk_mul_f32 v[26:27], v[30:31], v[30:31]
	v_ashrrev_i32_e32 v37, 31, v36
	v_max_f32_e32 v39, 0, v28
	v_fma_mixlo_f16 v28, v40, v40, 0
	v_cvt_pk_f16_f32 v27, v26, v27
	v_lshlrev_b64 v[36:37], 13, v[36:37]
	v_max_f32_e32 v41, 0, v29
	v_pack_b32_f16 v26, v28, v27
	v_pk_mul_f32 v[28:29], v[32:33], v[32:33]
	v_lshl_add_u64 v[36:37], s[0:1], 0, v[36:37]
	v_cvt_pk_f16_f32 v30, v28, v29
	v_pk_mul_f32 v[28:29], v[38:39], v[38:39]
	v_lshl_add_u64 v[36:37], v[36:37], 0, s[18:19]
	v_cvt_pk_f16_f32 v29, v28, v29
	v_lshl_add_u64 v[36:37], v[36:37], 0, s[92:93]
	v_alignbit_b32 v28, v29, v30, 16
	v_lshrrev_b32_e32 v29, 16, v29
	v_lshl_add_u64 v[36:37], v[36:37], 0, v[0:1]
	v_alignbit_b32 v27, v30, v27, 16
	v_fma_mixhi_f16 v29, v41, v41, 0
	v_pk_mul_f32 v[24:25], v[24:25], v[34:35] op_sel_hi:[1,0]
	v_pk_mul_f32 v[22:23], v[22:23], v[34:35] op_sel_hi:[1,0]
	global_store_dwordx4 v[36:37], v[26:29], off nt
	v_pk_mul_f32 v[18:19], v[18:19], v[34:35] op_sel_hi:[1,0]
	v_pk_mul_f32 v[20:21], v[20:21], v[34:35] op_sel_hi:[1,0]
	v_max_f32_e32 v28, 0, v22
	v_max_f32_e32 v22, 0, v23
	v_max_f32_e32 v23, 0, v24
	v_max_f32_e32 v24, 0, v25
	v_max_f32_e32 v25, 0, v18
	v_max_f32_e32 v26, 0, v19
	v_pk_mul_f32 v[18:19], v[22:23], v[22:23]
	v_max_f32_e32 v27, 0, v20
	v_fma_mixlo_f16 v20, v28, v28, 0
	v_cvt_pk_f16_f32 v19, v18, v19
	v_max_f32_e32 v29, 0, v21
	v_pack_b32_f16 v18, v20, v19
	v_pk_mul_f32 v[20:21], v[24:25], v[24:25]
	s_nop 0
	v_cvt_pk_f16_f32 v22, v20, v21
	v_pk_mul_f32 v[20:21], v[26:27], v[26:27]
	v_alignbit_b32 v19, v22, v19, 16
	v_cvt_pk_f16_f32 v21, v20, v21
	v_alignbit_b32 v20, v21, v22, 16
	v_lshrrev_b32_e32 v21, 16, v21
	v_fma_mixhi_f16 v21, v29, v29, 0
	global_store_dwordx4 v[36:37], v[18:21], off offset:256 nt
	s_nop 1
	v_mov_b32_e32 v20, v35
	v_pk_mul_f32 v[14:15], v[14:15], v[20:21] op_sel_hi:[1,0]
	v_pk_mul_f32 v[16:17], v[16:17], v[20:21] op_sel_hi:[1,0]
	v_max_f32_e32 v21, 0, v14
	v_max_f32_e32 v14, 0, v15
	v_max_f32_e32 v15, 0, v16
	v_pk_mul_f32 v[10:11], v[10:11], v[20:21] op_sel_hi:[1,0]
	v_add_u32_e32 v18, s11, v157
	v_max_f32_e32 v16, 0, v17
	v_pk_mul_f32 v[12:13], v[12:13], v[20:21] op_sel_hi:[1,0]
	v_max_f32_e32 v17, 0, v10
	v_max_f32_e32 v22, 0, v11
	v_pk_mul_f32 v[10:11], v[14:15], v[14:15]
	v_ashrrev_i32_e32 v19, 31, v18
	v_max_f32_e32 v23, 0, v12
	v_fma_mixlo_f16 v12, v21, v21, 0
	v_cvt_pk_f16_f32 v11, v10, v11
	v_lshlrev_b64 v[18:19], 13, v[18:19]
	v_max_f32_e32 v24, 0, v13
	v_pack_b32_f16 v10, v12, v11
	v_pk_mul_f32 v[12:13], v[16:17], v[16:17]
	v_lshl_add_u64 v[18:19], s[0:1], 0, v[18:19]
	v_cvt_pk_f16_f32 v14, v12, v13
	v_pk_mul_f32 v[12:13], v[22:23], v[22:23]
	v_lshl_add_u64 v[18:19], v[18:19], 0, s[18:19]
	v_cvt_pk_f16_f32 v13, v12, v13
	v_lshl_add_u64 v[18:19], v[18:19], 0, s[92:93]
	v_alignbit_b32 v12, v13, v14, 16
	v_lshrrev_b32_e32 v13, 16, v13
	v_lshl_add_u64 v[18:19], v[18:19], 0, v[0:1]
	v_alignbit_b32 v11, v14, v11, 16
	v_fma_mixhi_f16 v13, v24, v24, 0
	v_pk_mul_f32 v[8:9], v[8:9], v[20:21] op_sel_hi:[1,0]
	v_pk_mul_f32 v[6:7], v[6:7], v[20:21] op_sel_hi:[1,0]
	global_store_dwordx4 v[18:19], v[10:13], off nt
	v_pk_mul_f32 v[2:3], v[2:3], v[20:21] op_sel_hi:[1,0]
	v_pk_mul_f32 v[4:5], v[4:5], v[20:21] op_sel_hi:[1,0]
	v_max_f32_e32 v12, 0, v6
	v_max_f32_e32 v6, 0, v7
	v_max_f32_e32 v7, 0, v8
	v_max_f32_e32 v8, 0, v9
	v_max_f32_e32 v9, 0, v2
	v_max_f32_e32 v10, 0, v3
	v_pk_mul_f32 v[2:3], v[6:7], v[6:7]
	v_max_f32_e32 v11, 0, v4
	v_fma_mixlo_f16 v4, v12, v12, 0
	v_cvt_pk_f16_f32 v3, v2, v3
	v_max_f32_e32 v13, 0, v5
	v_pack_b32_f16 v2, v4, v3
	v_pk_mul_f32 v[4:5], v[8:9], v[8:9]
	s_mov_b64 s[18:19], s[14:15]
	v_cvt_pk_f16_f32 v6, v4, v5
	v_pk_mul_f32 v[4:5], v[10:11], v[10:11]
	v_alignbit_b32 v3, v6, v3, 16
	v_cvt_pk_f16_f32 v5, v4, v5
	v_alignbit_b32 v4, v5, v6, 16
	v_lshrrev_b32_e32 v5, 16, v5
	v_fma_mixhi_f16 v5, v13, v13, 0
	global_store_dwordx4 v[18:19], v[2:5], off offset:256 nt
	s_cbranch_vccz .LBB0_2466
	s_waitcnt vmcnt(0)
	s_cmpk_gt_u32 s2, 0xff
	s_cbranch_scc1 .LBB0_2477
	s_barrier
